# S5 plus: softmax-finish cvt/permlane woven into the QK MFMAs, LDS waits batched per read burst, DMA nops dropped
# baseline (speedup 1.0000x reference)
; __device__ __forceinline__ void finishSM(f32x16& p0, f32x16& p1, float alpha, float& l_reg, bf16x8& pa0, bf16x8& pa1, bf16x8& pa2, bf16x8& pa3) {
;   for (int r = 0; r < 16; ++r) p1[r] = __builtin_amdgcn_exp2f(p1[r]);
;   float ps = 0; for (int r = 0; r < 16; ++r) ps += p0[r]; for (int r = 0; r < 16; ++r) ps += p1[r];
;   { auto rr = __builtin_amdgcn_permlane32_swap(__float_as_uint(ps), __float_as_uint(ps), false, false);
;     ps = __uint_as_float(rr[0]) + __uint_as_float(rr[1]); }
;   l_reg = l_reg * alpha + ps;
;     ...
;   PK4(p0, 0, pa0); PK4(p0, 8, pa1); PK4(p1, 0, pa2); PK4(p1, 8, pa3);
;     ...
; }
; __device__ __forceinline__ void kload(bf16x8 (&kf)[8], const char* Ks, int r32, int hi, int sb) {
; #pragma unroll
;   for (int d0 = 0; d0 < 4; ++d0) { const int cb = sb + (d0 * 16 + hi * 8) * 2;
;     kf[2 * d0] = *reinterpret_cast<const bf16x8*>(Ks + KSWZ(r32, cb)); kf[2 * d0 + 1] = *reinterpret_cast<const bf16x8*>(Ks + KSWZ(32 + r32, cb)); }
; }
; __device__ __forceinline__ void kmma(f32x16& p0, f32x16& p1, const bf16x8 (&kf)[8], const bf16x8* qr) {
;   asm volatile("s_waitcnt lgkmcnt(0)" ::: "memory"); SBAR();
;   p0 = f32x16{}; p1 = f32x16{};
; #pragma unroll
;   for (int d0 = 0; d0 < 4; ++d0) { p0 = __builtin_amdgcn_mfma_f32_32x32x16_bf16(kf[2 * d0], qr[d0], p0, 0, 0, 0); p1 = __builtin_amdgcn_mfma_f32_32x32x16_bf16(kf[2 * d0 + 1], qr[d0], p1, 0, 0, 0); }
; }
; __device__ __forceinline__ void qkt(f32x16& p0, f32x16& p1, const char* Ks, const bf16x8* qr, int r32, int hi, int sb) {
;   bf16x8 kf[8]; kload(kf, Ks, r32, hi, sb); SBAR(); kmma(p0, p1, kf, qr);
; }
; __device__ __forceinline__ int v_st(int k, int c) { const int kk = (k & ~0xC) | ((k & 4) << 1) | ((k & 8) >> 1); return ((kk >> 3) * 4 + (c >> 5)) * 512 + ((kk & 7) * 32 + (c & 31)) * 2; }
; __device__ __forceinline__ int v_rd_base(int lane) { return ((lane & 3) << 3) | (((lane >> 2) & 3) << 6) | (((lane >> 4) & 1) << 5) | (((lane >> 5) & 1) << 8); }
; template <int OFF> __device__ __forceinline__ s16x4 tr_read(int vb) {
;   s16x4 r; asm volatile("ds_read_b64_tr_b16 %0, %1 offset:%2" : "=&v"(r) : "v"(vb), "i"(OFF) : "memory"); return r;
; }
; template <int D0> __device__ __forceinline__ void v_frag_read(VFrag& f, int vb) {
;   f.l0 = tr_read<v_rd_off(D0, 0, 0)>(vb); f.h0 = tr_read<v_rd_off(D0, 0, 1)>(vb); f.l1 = tr_read<v_rd_off(D0, 1, 0)>(vb); f.h1 = tr_read<v_rd_off(D0, 1, 1)>(vb);
.LBB0_770:
	s_and_b32 s0, s12, 0xff
	s_mulk_i32 s0, 0xab
	s_lshr_b32 s0, s0, 9
	s_mul_i32 s0, s0, 3
	s_sub_i32 s0, s12, s0
	s_and_b32 s0, s0, 0xff
	s_lshl_b32 s0, s0, 14
	s_add_i32 s0, s0, 0
	v_add_u32_e32 v86, s0, v169
	v_add_u32_e32 v90, s0, v170
	ds_read_b128 v[82:85], v86
	ds_read_b128 v[86:89], v86 offset:8192
	ds_read_b128 v[130:133], v90
	ds_read_b128 v[134:137], v90 offset:8192
	v_add_u32_e32 v90, s0, v171
	ds_read_b128 v[206:209], v90
	ds_read_b128 v[210:213], v90 offset:8192
	v_add_u32_e32 v90, s0, v172
	ds_read_b128 v[214:217], v90
	ds_read_b128 v[218:221], v90 offset:8192
	s_and_b32 s13, s36, 0xc000
	v_add_u32_e32 v244, s13, v164
	ds_read_b64_tr_b16 v[228:229], v244 offset:0
	ds_read_b64_tr_b16 v[230:231], v244 offset:0x800
	ds_read_b64_tr_b16 v[232:233], v244 offset:0x1000
	ds_read_b64_tr_b16 v[234:235], v244 offset:0x1800
	ds_read_b64_tr_b16 v[236:237], v244 offset:0x2000
	ds_read_b64_tr_b16 v[238:239], v244 offset:0x2800
	ds_read_b64_tr_b16 v[240:241], v244 offset:0x3000
	ds_read_b64_tr_b16 v[242:243], v244 offset:0x3800
	v_exp_f32_e32 v148, v66
	v_add_f32_e32 v66, 0, v175
	v_add_f32_e32 v66, v177, v66
	v_add_f32_e32 v66, v192, v66
	v_add_f32_e32 v66, v195, v66
	v_add_f32_e32 v66, v196, v66
	v_add_f32_e32 v66, v199, v66
	v_add_f32_e32 v66, v200, v66
	v_add_f32_e32 v66, v203, v66
	v_add_f32_e32 v66, v176, v66
	v_add_f32_e32 v66, v193, v66
	v_add_f32_e32 v66, v194, v66
	v_add_f32_e32 v66, v197, v66
	v_add_f32_e32 v66, v198, v66
	v_exp_f32_e32 v149, v67
	v_add_f32_e32 v66, v201, v66
	s_waitcnt lgkmcnt(0)
	v_mfma_f32_32x32x16_bf16 v[98:113], v[82:85], v[126:129], 0
	v_exp_f32_e32 v150, v68
	s_add_i32 s37, s12, 2
	v_add_f32_e32 v66, v202, v66
	s_cmpk_lt_u32 s12, 0x7e
	v_exp_f32_e32 v151, v69
	s_cselect_b64 s[0:1], -1, 0
	v_add_f32_e32 v66, v204, v66
	s_and_b64 s[10:11], s[0:1], exec
	v_exp_f32_e32 v186, v70
	s_cselect_b32 s10, 0, 0xffffff80
	v_add_f32_e32 v66, v148, v66
	v_exp_f32_e32 v187, v71
	v_mfma_f32_32x32x16_bf16 v[82:97], v[86:89], v[126:129], 0
	v_add_f32_e32 v66, v149, v66
	s_add_i32 s58, s37, s10
	v_exp_f32_e32 v188, v72
	s_and_b64 s[0:1], s[0:1], exec
	v_add_f32_e32 v66, v150, v66
	s_cselect_b32 s1, s9, s30
	v_exp_f32_e32 v189, v73
	s_cselect_b32 s0, s8, s26
	v_add_f32_e32 v66, v151, v66
	s_lshl_b64 s[10:11], s[58:59], 17
	v_exp_f32_e32 v205, v74
	v_add_f32_e32 v66, v186, v66
	v_mfma_f32_32x32x16_bf16 v[98:113], v[130:133], v[122:125], v[98:113]
	v_exp_f32_e32 v222, v75
	s_lshl_b64 s[0:1], s[0:1], 11
	v_add_f32_e32 v66, v187, v66
	s_add_u32 s10, s10, s0
	v_exp_f32_e32 v223, v76
	s_addc_u32 s11, s11, s1
	v_add_f32_e32 v66, v188, v66
	s_add_u32 s0, s20, s10
	v_exp_f32_e32 v224, v77
	s_addc_u32 s1, s21, s11
	v_add_f32_e32 v66, v189, v66
	v_exp_f32_e32 v225, v78
	v_mfma_f32_32x32x16_bf16 v[82:97], v[134:137], v[122:125], v[82:97]
	v_add_f32_e32 v66, v205, v66
	s_add_u32 s10, s22, s10
	v_exp_f32_e32 v226, v79
	s_addc_u32 s11, s23, s11
	v_add_f32_e32 v66, v222, v66
	s_and_b32 s13, s37, 0xff
	v_exp_f32_e32 v227, v80
	s_mulk_i32 s13, 0xab
	v_add_f32_e32 v66, v223, v66
	s_lshr_b32 s13, s13, 9
	v_exp_f32_e32 v81, v81
	v_add_f32_e32 v66, v224, v66
	v_add_f32_e32 v66, v225, v66
	v_mfma_f32_32x32x16_bf16 v[98:113], v[206:209], v[118:121], v[98:113]
	v_add_f32_e32 v66, v226, v66
	s_mul_i32 s13, s13, 3
	v_add_f32_e32 v66, v227, v66
	s_sub_i32 s13, s37, s13
	v_add_f32_e32 v130, v81, v66
	s_and_b32 s13, s13, 0xff
	v_mov_b32_e32 v131, v130
	s_lshl_b32 s13, s13, 14
	v_cvt_pk_bf16_f32 v66, v175, v177
	s_add_i32 s42, s36, 0xffffc000
	v_cvt_pk_bf16_f32 v67, v192, v195
	v_cvt_pk_bf16_f32 v68, v196, v199
	v_mfma_f32_32x32x16_bf16 v[82:97], v[210:213], v[118:121], v[82:97]
	v_permlane32_swap_b32_e32 v130, v131
	s_and_b32 s42, s42, 0xc000
	v_cvt_pk_bf16_f32 v69, v200, v203
	s_add_i32 s13, s13, s27
	v_permlane32_swap_b32_e32 v66, v68
	s_add_i32 s42, s42, s31
	v_cvt_pk_bf16_f32 v70, v176, v193
	v_lshl_add_u64 v[246:247], s[0:1], 0, v[146:147]
	v_cvt_pk_bf16_f32 v71, v194, v197
	s_mov_b32 m0, s13
	v_cvt_pk_bf16_f32 v72, v198, v201
	v_cvt_pk_bf16_f32 v73, v202, v204
	v_mfma_f32_32x32x16_bf16 v[98:113], v[214:217], v[114:117], v[98:113]
	v_cvt_pk_bf16_f32 v74, v148, v149
	global_load_lds_dwordx4 v[246:247], off
	v_cvt_pk_bf16_f32 v75, v150, v151
	v_lshl_add_u64 v[246:247], s[10:11], 0, v[142:143]
	v_cvt_pk_bf16_f32 v76, v186, v187
	s_mov_b32 m0, s42
	v_cvt_pk_bf16_f32 v77, v188, v189
	global_load_lds_dwordx4 v[246:247], off
	v_cvt_pk_bf16_f32 v78, v205, v222
	v_lshl_add_u64 v[246:247], s[0:1], 0, v[144:145]
	v_cvt_pk_bf16_f32 v79, v223, v224
	v_cvt_pk_bf16_f32 v80, v225, v226
	v_mfma_f32_32x32x16_bf16 v[82:97], v[218:221], v[114:117], v[82:97]
	v_cvt_pk_bf16_f32 v81, v227, v81
	s_add_i32 m0, s13, 0x2000
	v_permlane32_swap_b32_e32 v67, v69
	global_load_lds_dwordx4 v[246:247], off
	v_permlane32_swap_b32_e32 v70, v72
	v_lshl_add_u64 v[246:247], s[10:11], 0, v[154:155]
	v_permlane32_swap_b32_e32 v71, v73
	s_add_i32 m0, s42, 0x2000
	v_permlane32_swap_b32_e32 v74, v76
	global_load_lds_dwordx4 v[246:247], off
	v_permlane32_swap_b32_e32 v75, v77
	v_permlane32_swap_b32_e32 v78, v80
	v_permlane32_swap_b32_e32 v79, v81
	ds_read_b64_tr_b16 v[204:205], v244 offset:0x200
	ds_read_b64_tr_b16 v[206:207], v244 offset:0xa00
	ds_read_b64_tr_b16 v[208:209], v244 offset:0x1200
	ds_read_b64_tr_b16 v[210:211], v244 offset:0x1a00
	ds_read_b64_tr_b16 v[212:213], v244 offset:0x2200
	ds_read_b64_tr_b16 v[214:215], v244 offset:0x2a00
	ds_read_b64_tr_b16 v[216:217], v244 offset:0x3200
	ds_read_b64_tr_b16 v[218:219], v244 offset:0x3a00
	v_mfma_f32_32x32x16_bf16 v[18:33], v[66:69], v[228:231], v[18:33]
	v_max_f32_e32 v245, v99, v99
	v_max_f32_e32 v246, v98, v98
; __device__ __forceinline__ void partialSM(f32x16& p0, f32x16& p1, float& m_reg, float& mn, float& alpha) {
;   constexpr float C = SCALE * 1.4426950408889634f;
;   float pmax = p0[0]; for (int r = 1; r < 16; ++r) pmax = fmaxf(pmax, p0[r]); for (int r = 0; r < 16; ++r) pmax = fmaxf(pmax, p1[r]);
;   { auto rr = __builtin_amdgcn_permlane32_swap(__float_as_uint(pmax), __float_as_uint(pmax), false, false);
;     pmax = fmaxf(__uint_as_float(rr[0]), __uint_as_float(rr[1])); }
;   if (__builtin_expect(__all(pmax - m_reg <= THR / SCALE), 1)) { mn = m_reg; alpha = 1.f; }
;   else { mn = fmaxf(m_reg, pmax); alpha = __builtin_amdgcn_exp2f((m_reg - mn) * C); m_reg = mn; }
;   float mnC = -mn * C;
;   for (int r = 0; r < 16; ++r) p0[r] = fmaf(p0[r], C, mnC); for (int r = 0; r < 16; ++r) p1[r] = fmaf(p1[r], C, mnC);
;   for (int r = 0; r < 16; ++r) p0[r] = __builtin_amdgcn_exp2f(p0[r]);
; }
; template <int D0> __device__ __forceinline__ void v_frag_read(VFrag& f, int vb) {
;   f.l0 = tr_read<v_rd_off(D0, 0, 0)>(vb); f.h0 = tr_read<v_rd_off(D0, 0, 1)>(vb); f.l1 = tr_read<v_rd_off(D0, 1, 0)>(vb); f.h1 = tr_read<v_rd_off(D0, 1, 1)>(vb);
;   f.l2 = tr_read<v_rd_off(D0, 2, 0)>(vb); f.h2 = tr_read<v_rd_off(D0, 2, 1)>(vb); f.l3 = tr_read<v_rd_off(D0, 3, 0)>(vb); f.h3 = tr_read<v_rd_off(D0, 3, 1)>(vb);
; }
; __device__ __forceinline__ void pv_mma(f32x16& od, const VFrag& f, bf16x8 pa0, bf16x8 pa1, bf16x8 pa2, bf16x8 pa3) {
;     ...
;   od = __builtin_amdgcn_mfma_f32_32x32x16_bf16(pa0, PK(f.l0, f.h0), od, 0, 0, 0);
;   od = __builtin_amdgcn_mfma_f32_32x32x16_bf16(pa1, PK(f.l1, f.h1), od, 0, 0, 0);
;   od = __builtin_amdgcn_mfma_f32_32x32x16_bf16(pa2, PK(f.l2, f.h2), od, 0, 0, 0);
;   od = __builtin_amdgcn_mfma_f32_32x32x16_bf16(pa3, PK(f.l3, f.h3), od, 0, 0, 0);
;     ...
; }
; __device__ __forceinline__ void pv_d0(f32x16* o, int vb, bf16x8 pa0, bf16x8 pa1, bf16x8 pa2, bf16x8 pa3) {
;   VFrag fa, fb;
;   v_frag_read<0>(fa, vb);
;   asm volatile("s_waitcnt lgkmcnt(0)" ::: "memory"); SBAR();
;   v_frag_read<1>(fb, vb); SBAR();
;   pv_mma(o[0], fa, pa0, pa1, pa2, pa3); SBAR();
;   asm volatile("s_waitcnt lgkmcnt(0)" ::: "memory"); SBAR();
;   v_frag_read<2>(fa, vb); SBAR();
;   pv_mma(o[1], fb, pa0, pa1, pa2, pa3); SBAR();
;   asm volatile("s_waitcnt lgkmcnt(0)" ::: "memory"); SBAR();
;   v_frag_read<3>(fb, vb); SBAR();
;   pv_mma(o[2], fa, pa0, pa1, pa2, pa3); SBAR();
	v_max_f32_e32 v245, v246, v245
	v_max3_f32 v245, v245, v100, v101
	v_max3_f32 v245, v245, v102, v103
	v_max3_f32 v245, v245, v104, v105
	v_max3_f32 v245, v245, v106, v107
	v_max3_f32 v245, v245, v108, v109
	v_mfma_f32_32x32x16_bf16 v[18:33], v[70:73], v[232:235], v[18:33]
	v_max3_f32 v245, v245, v110, v111
	v_max3_f32 v245, v245, v112, v113
	v_max3_f32 v245, v245, v82, v83
	v_max3_f32 v245, v245, v84, v85
	v_max3_f32 v245, v245, v86, v87
	v_max3_f32 v245, v245, v88, v89
	v_max3_f32 v245, v245, v90, v91
	v_max3_f32 v245, v245, v92, v93
	v_mfma_f32_32x32x16_bf16 v[18:33], v[74:77], v[236:239], v[18:33]
	v_max3_f32 v245, v245, v94, v95
	v_max3_f32 v245, v245, v96, v97
	v_mov_b32_e32 v246, v245
	s_nop 1
	v_permlane32_swap_b32_e32 v245, v246
	v_max_f32_e32 v246, v246, v246
	v_max_f32_e32 v245, v245, v245
	v_max_f32_e32 v245, v245, v246
	v_sub_f32_e32 v246, v245, v174
	v_mfma_f32_32x32x16_bf16 v[18:33], v[78:81], v[240:243], v[18:33]
	v_cmp_ge_f32_e32 vcc, s63, v246
	v_max_f32_e32 v246, v174, v174
	v_max_f32_e32 v245, v246, v245
	v_sub_f32_e32 v246, v174, v245
	v_mul_f32_e32 v246, 0x3e38aa3b, v246
	v_exp_f32_e32 v246, v246
	s_cmp_eq_u64 vcc, exec
	s_cselect_b64 s[0:1], -1, 0
	v_cndmask_b32_e64 v132, v246, 1.0, s[0:1]
	ds_read_b64_tr_b16 v[228:229], v244 offset:0x400
	ds_read_b64_tr_b16 v[230:231], v244 offset:0xc00
	ds_read_b64_tr_b16 v[232:233], v244 offset:0x1400
	ds_read_b64_tr_b16 v[234:235], v244 offset:0x1c00
	ds_read_b64_tr_b16 v[236:237], v244 offset:0x2400
	ds_read_b64_tr_b16 v[238:239], v244 offset:0x2c00
	ds_read_b64_tr_b16 v[240:241], v244 offset:0x3400
	ds_read_b64_tr_b16 v[242:243], v244 offset:0x3c00
	v_cndmask_b32_e64 v133, v245, v174, s[0:1]
	v_mul_f32_e32 v148, 0xbe38aa3b, v133
	s_waitcnt lgkmcnt(8)
	v_mfma_f32_32x32x16_bf16 v[50:65], v[66:69], v[204:207], v[50:65]
	v_fmamk_f32 v98, v98, 0x3e38aa3b, v148
	v_fmamk_f32 v99, v99, 0x3e38aa3b, v148
	v_fmamk_f32 v100, v100, 0x3e38aa3b, v148
	v_fmamk_f32 v101, v101, 0x3e38aa3b, v148
	v_mfma_f32_32x32x16_bf16 v[50:65], v[70:73], v[208:211], v[50:65]
	v_fmamk_f32 v102, v102, 0x3e38aa3b, v148
	v_fmamk_f32 v103, v103, 0x3e38aa3b, v148
	v_fmamk_f32 v104, v104, 0x3e38aa3b, v148
	v_fmamk_f32 v105, v105, 0x3e38aa3b, v148
	v_mfma_f32_32x32x16_bf16 v[50:65], v[74:77], v[212:215], v[50:65]
	v_fmamk_f32 v106, v106, 0x3e38aa3b, v148
	v_fmamk_f32 v107, v107, 0x3e38aa3b, v148
	v_fmamk_f32 v108, v108, 0x3e38aa3b, v148
	v_fmamk_f32 v109, v109, 0x3e38aa3b, v148
	v_mfma_f32_32x32x16_bf16 v[50:65], v[78:81], v[216:219], v[50:65]
	v_fmamk_f32 v110, v110, 0x3e38aa3b, v148
	v_fmamk_f32 v111, v111, 0x3e38aa3b, v148
	v_fmamk_f32 v112, v112, 0x3e38aa3b, v148
	v_fmamk_f32 v113, v113, 0x3e38aa3b, v148
	ds_read_b64_tr_b16 v[204:205], v244 offset:0x600
	ds_read_b64_tr_b16 v[206:207], v244 offset:0xe00
	ds_read_b64_tr_b16 v[208:209], v244 offset:0x1600
	ds_read_b64_tr_b16 v[210:211], v244 offset:0x1e00
	ds_read_b64_tr_b16 v[212:213], v244 offset:0x2600
	ds_read_b64_tr_b16 v[214:215], v244 offset:0x2e00
	ds_read_b64_tr_b16 v[216:217], v244 offset:0x3600
	ds_read_b64_tr_b16 v[218:219], v244 offset:0x3e00
	s_waitcnt lgkmcnt(8)
	v_mfma_f32_32x32x16_bf16 v[34:49], v[66:69], v[228:231], v[34:49]
	v_fmamk_f32 v82, v82, 0x3e38aa3b, v148
	v_fmamk_f32 v83, v83, 0x3e38aa3b, v148
	v_fmamk_f32 v84, v84, 0x3e38aa3b, v148
	v_fmamk_f32 v85, v85, 0x3e38aa3b, v148
	v_mfma_f32_32x32x16_bf16 v[34:49], v[70:73], v[232:235], v[34:49]
	v_fmamk_f32 v86, v86, 0x3e38aa3b, v148
	v_fmamk_f32 v87, v87, 0x3e38aa3b, v148
	s_add_i32 s13, s36, 0xffff4000
	v_fmamk_f32 v149, v88, 0x3e38aa3b, v148
	v_mfma_f32_32x32x16_bf16 v[34:49], v[74:77], v[236:239], v[34:49]
	v_fmamk_f32 v150, v89, 0x3e38aa3b, v148
	v_fmamk_f32 v151, v90, 0x3e38aa3b, v148
	v_fmamk_f32 v186, v91, 0x3e38aa3b, v148
	v_fmamk_f32 v187, v92, 0x3e38aa3b, v148
	v_mfma_f32_32x32x16_bf16 v[34:49], v[78:81], v[240:243], v[34:49]
	v_fmamk_f32 v188, v93, 0x3e38aa3b, v148
	v_fmamk_f32 v189, v94, 0x3e38aa3b, v148
	v_exp_f32_e32 v192, v98
	v_exp_f32_e32 v193, v99
	v_exp_f32_e32 v194, v100
	v_exp_f32_e32 v195, v101
	s_waitcnt lgkmcnt(0)
	v_mfma_f32_32x32x16_bf16 v[2:17], v[66:69], v[204:207], v[2:17]
	v_exp_f32_e32 v196, v102
	v_exp_f32_e32 v197, v103
	v_exp_f32_e32 v198, v104
	v_exp_f32_e32 v199, v105
	v_mfma_f32_32x32x16_bf16 v[2:17], v[70:73], v[208:211], v[2:17]
	v_exp_f32_e32 v200, v106
	v_exp_f32_e32 v201, v107
	v_exp_f32_e32 v202, v108
	v_exp_f32_e32 v203, v109
	v_exp_f32_e32 v204, v110
	v_exp_f32_e32 v205, v111
	v_mfma_f32_32x32x16_bf16 v[2:17], v[74:77], v[212:215], v[2:17]
	v_exp_f32_e32 v206, v112
	v_exp_f32_e32 v207, v113
	v_fmamk_f32 v208, v95, 0x3e38aa3b, v148
	v_fmamk_f32 v209, v96, 0x3e38aa3b, v148
	v_fmac_f32_e32 v148, 0x3e38aa3b, v97
	v_mfma_f32_32x32x16_bf16 v[2:17], v[78:81], v[216:219], v[2:17]
	v_cmp_gt_f32_e32 vcc, 1.0, v132
	s_cbranch_vccz .LBB0_774
	s_and_saveexec_b64 s[10:11], s[40:41]
	ds_write_b32 v162, v132 offset:128
	s_or_b64 exec, exec, s[10:11]
	s_waitcnt lgkmcnt(0)
	v_add_u32_e32 v67, s18, v140
	ds_read_b128 v[68:71], v67 offset:224
	ds_read_b128 v[72:75], v67 offset:192
	ds_read_b128 v[76:79], v67 offset:160
	ds_read_b128 v[134:137], v67 offset:128
	s_waitcnt lgkmcnt(0)
	v_pk_mul_f32 v[30:31], v[30:31], v[68:69]
	v_pk_mul_f32 v[26:27], v[26:27], v[72:73]
	v_pk_mul_f32 v[22:23], v[22:23], v[76:77]
	v_pk_mul_f32 v[32:33], v[32:33], v[70:71]
	v_pk_mul_f32 v[28:29], v[28:29], v[74:75]
	v_pk_mul_f32 v[24:25], v[24:25], v[78:79]
	v_pk_mul_f32 v[20:21], v[20:21], v[136:137]
	v_pk_mul_f32 v[18:19], v[18:19], v[134:135]
	v_pk_mul_f32 v[62:63], v[62:63], v[68:69]
	v_pk_mul_f32 v[58:59], v[58:59], v[72:73]
	v_pk_mul_f32 v[54:55], v[54:55], v[76:77]
	v_pk_mul_f32 v[64:65], v[64:65], v[70:71]
	v_pk_mul_f32 v[60:61], v[60:61], v[74:75]
	v_pk_mul_f32 v[56:57], v[56:57], v[78:79]
	v_pk_mul_f32 v[52:53], v[52:53], v[136:137]
	v_pk_mul_f32 v[50:51], v[50:51], v[134:135]
	v_pk_mul_f32 v[46:47], v[46:47], v[68:69]
	v_pk_mul_f32 v[42:43], v[42:43], v[72:73]
	v_pk_mul_f32 v[38:39], v[38:39], v[76:77]
	v_pk_mul_f32 v[48:49], v[48:49], v[70:71]
	v_pk_mul_f32 v[44:45], v[44:45], v[74:75]
	v_pk_mul_f32 v[40:41], v[40:41], v[78:79]
	v_pk_mul_f32 v[36:37], v[36:37], v[136:137]
	v_pk_mul_f32 v[34:35], v[34:35], v[134:135]
	v_pk_mul_f32 v[14:15], v[14:15], v[68:69]
	v_pk_mul_f32 v[10:11], v[10:11], v[72:73]
	v_pk_mul_f32 v[6:7], v[6:7], v[76:77]
	v_pk_mul_f32 v[16:17], v[16:17], v[70:71]
	v_pk_mul_f32 v[12:13], v[12:13], v[74:75]
	v_pk_mul_f32 v[8:9], v[8:9], v[78:79]
	v_pk_mul_f32 v[4:5], v[4:5], v[136:137]
	v_pk_mul_f32 v[2:3], v[2:3], v[134:135]
; #define SBAR() __builtin_amdgcn_sched_barrier(0)
; __device__ __forceinline__ void finishSM(f32x16& p0, f32x16& p1, float alpha, float& l_reg, bf16x8& pa0, bf16x8& pa1, bf16x8& pa2, bf16x8& pa3) {
;   for (int r = 0; r < 16; ++r) p1[r] = __builtin_amdgcn_exp2f(p1[r]);
;   float ps = 0; for (int r = 0; r < 16; ++r) ps += p0[r]; for (int r = 0; r < 16; ++r) ps += p1[r];
;   { auto rr = __builtin_amdgcn_permlane32_swap(__float_as_uint(ps), __float_as_uint(ps), false, false);
;     ps = __uint_as_float(rr[0]) + __uint_as_float(rr[1]); }
;   l_reg = l_reg * alpha + ps;
;     ...
;   PK4(p0, 0, pa0); PK4(p0, 8, pa1); PK4(p1, 0, pa2); PK4(p1, 8, pa3);
;     ...
; }
; __device__ __forceinline__ void kload(bf16x8 (&kf)[8], const char* Ks, int r32, int hi, int sb) {
; #pragma unroll
;   for (int d0 = 0; d0 < 4; ++d0) { const int cb = sb + (d0 * 16 + hi * 8) * 2;
;     kf[2 * d0] = *reinterpret_cast<const bf16x8*>(Ks + KSWZ(r32, cb)); kf[2 * d0 + 1] = *reinterpret_cast<const bf16x8*>(Ks + KSWZ(32 + r32, cb)); }
; }
; __device__ __forceinline__ void kmma(f32x16& p0, f32x16& p1, const bf16x8 (&kf)[8], const bf16x8* qr) {
;   asm volatile("s_waitcnt lgkmcnt(0)" ::: "memory"); SBAR();
;   p0 = f32x16{}; p1 = f32x16{};
; #pragma unroll
;   for (int d0 = 0; d0 < 4; ++d0) { p0 = __builtin_amdgcn_mfma_f32_32x32x16_bf16(kf[2 * d0], qr[d0], p0, 0, 0, 0); p1 = __builtin_amdgcn_mfma_f32_32x32x16_bf16(kf[2 * d0 + 1], qr[d0], p1, 0, 0, 0); }
; }
; __device__ __forceinline__ void qkt(f32x16& p0, f32x16& p1, const char* Ks, const bf16x8* qr, int r32, int hi, int sb) {
;   bf16x8 kf[8]; kload(kf, Ks, r32, hi, sb); SBAR(); kmma(p0, p1, kf, qr);
; }
.LBB0_774:
	s_waitcnt vmcnt(4)
	s_barrier
	s_and_b32 s46, s13, 0xc000
	v_add_u32_e32 v244, s46, v164
	s_add_i32 s0, s12, 1
	s_mul_i32 s1, s0, 0xab
	s_bfe_u32 s1, s1, 0x70009
	s_mul_i32 s1, s1, 3
	s_sub_i32 s0, s0, s1
	s_and_b32 s0, s0, 0xff
	s_lshl_b32 s0, s0, 14
	s_add_i32 s0, s0, 0
	v_add_u32_e32 v70, s0, v169
	v_add_u32_e32 v74, s0, v170
	ds_read_b128 v[66:69], v70
	ds_read_b128 v[70:73], v70 offset:8192
	ds_read_b128 v[98:101], v74
	ds_read_b128 v[102:105], v74 offset:8192
	v_add_u32_e32 v74, s0, v171
	ds_read_b128 v[106:109], v74
	ds_read_b128 v[110:113], v74 offset:8192
	v_add_u32_e32 v74, s0, v172
	ds_read_b128 v[134:137], v74
	ds_read_b128 v[174:177], v74 offset:8192
	ds_read_b64_tr_b16 v[228:229], v244 offset:0
	ds_read_b64_tr_b16 v[230:231], v244 offset:0x800
	ds_read_b64_tr_b16 v[232:233], v244 offset:0x1000
	ds_read_b64_tr_b16 v[234:235], v244 offset:0x1800
	ds_read_b64_tr_b16 v[236:237], v244 offset:0x2000
	ds_read_b64_tr_b16 v[238:239], v244 offset:0x2800
	ds_read_b64_tr_b16 v[240:241], v244 offset:0x3000
	ds_read_b64_tr_b16 v[242:243], v244 offset:0x3800
	v_exp_f32_e32 v210, v82
	v_exp_f32_e32 v211, v83
	v_exp_f32_e32 v212, v84
	v_exp_f32_e32 v213, v85
	v_exp_f32_e32 v214, v86
	v_exp_f32_e32 v215, v87
	v_add_f32_e32 v216, 0, v192
	v_add_f32_e32 v216, v193, v216
	v_add_f32_e32 v216, v194, v216
	v_add_f32_e32 v216, v195, v216
	v_exp_f32_e32 v149, v149
	v_exp_f32_e32 v150, v150
	v_exp_f32_e32 v151, v151
	v_exp_f32_e32 v186, v186
	v_exp_f32_e32 v187, v187
	v_exp_f32_e32 v188, v188
	s_waitcnt lgkmcnt(0)
	v_mfma_f32_32x32x16_bf16 v[82:97], v[66:69], v[126:129], 0
	v_exp_f32_e32 v189, v189
	s_add_i32 s46, s12, 3
	v_exp_f32_e32 v208, v208
	s_cmpk_lt_u32 s12, 0x7d
	v_exp_f32_e32 v209, v209
	s_cselect_b64 s[42:43], -1, 0
	v_exp_f32_e32 v148, v148
	v_add_f32_e32 v248, v196, v216
	v_add_f32_e32 v248, v197, v248
	v_add_f32_e32 v248, v198, v248
	v_mfma_f32_32x32x16_bf16 v[66:81], v[70:73], v[126:129], 0
	v_add_f32_e32 v248, v199, v248
	s_and_b64 s[44:45], s[42:43], exec
	v_add_f32_e32 v248, v200, v248
	s_cselect_b32 s44, 0, 0xffffff80
	v_add_f32_e32 v248, v201, v248
	s_add_i32 s58, s46, s44
	v_add_f32_e32 v248, v202, v248
	v_add_f32_e32 v248, v203, v248
	v_add_f32_e32 v248, v204, v248
	v_add_f32_e32 v248, v205, v248
	v_mfma_f32_32x32x16_bf16 v[82:97], v[98:101], v[122:125], v[82:97]
	v_add_f32_e32 v248, v206, v248
	s_and_b64 s[42:43], s[42:43], exec
	v_add_f32_e32 v248, v207, v248
	s_cselect_b32 s43, s9, s30
	v_add_f32_e32 v248, v210, v248
	s_cselect_b32 s42, s8, s26
	v_add_f32_e32 v248, v211, v248
	v_add_f32_e32 v248, v212, v248
	v_add_f32_e32 v248, v213, v248
	v_add_f32_e32 v248, v214, v248
	v_mfma_f32_32x32x16_bf16 v[66:81], v[102:105], v[122:125], v[66:81]
	v_add_f32_e32 v248, v215, v248
	s_lshl_b64 s[44:45], s[58:59], 17
	v_add_f32_e32 v248, v149, v248
	s_lshl_b64 s[42:43], s[42:43], 11
	v_add_f32_e32 v248, v150, v248
	s_add_u32 s44, s44, s42
	v_add_f32_e32 v248, v151, v248
	s_addc_u32 s45, s45, s43
	v_add_f32_e32 v248, v186, v248
	v_add_f32_e32 v248, v187, v248
	v_add_f32_e32 v248, v188, v248
	v_add_f32_e32 v248, v189, v248
	v_mfma_f32_32x32x16_bf16 v[82:97], v[106:109], v[118:121], v[82:97]
	v_add_f32_e32 v248, v208, v248
	s_add_u32 s42, s20, s44
	v_add_f32_e32 v248, v209, v248
	s_addc_u32 s43, s21, s45
	v_add_f32_e32 v99, v148, v248
	s_add_u32 s44, s22, s44
	v_mov_b32_e32 v100, v99
	s_nop 1
	v_permlane32_swap_b32_e32 v99, v100
	v_cvt_pk_bf16_f32 v102, v192, v193
	v_cvt_pk_bf16_f32 v103, v194, v195
	v_mfma_f32_32x32x16_bf16 v[66:81], v[110:113], v[118:121], v[66:81]
	v_cvt_pk_bf16_f32 v104, v196, v197
	s_mul_i32 s47, s46, 0xab
	v_cvt_pk_bf16_f32 v105, v198, v199
	s_addc_u32 s45, s23, s45
	v_cvt_pk_bf16_f32 v106, v200, v201
	s_bfe_u32 s47, s47, 0x70009
	v_cvt_pk_bf16_f32 v107, v202, v203
	v_cvt_pk_bf16_f32 v108, v204, v205
	v_cvt_pk_bf16_f32 v109, v206, v207
	v_cvt_pk_bf16_f32 v110, v210, v211
	v_mfma_f32_32x32x16_bf16 v[82:97], v[134:137], v[114:117], v[82:97]
	v_cvt_pk_bf16_f32 v111, v212, v213
	s_mul_i32 s47, s47, 3
	v_cvt_pk_bf16_f32 v112, v214, v215
	s_sub_i32 s46, s46, s47
	v_cvt_pk_bf16_f32 v113, v149, v150
	s_and_b32 s46, s46, 0xff
	v_cvt_pk_bf16_f32 v134, v151, v186
	v_cvt_pk_bf16_f32 v135, v187, v188
	v_cvt_pk_bf16_f32 v136, v189, v208
	v_cvt_pk_bf16_f32 v137, v209, v148
	v_mfma_f32_32x32x16_bf16 v[66:81], v[174:177], v[114:117], v[66:81]
	v_permlane32_swap_b32_e32 v102, v104
	s_lshl_b32 s46, s46, 14
	v_permlane32_swap_b32_e32 v103, v105
	s_add_i32 s46, s46, s27
	v_permlane32_swap_b32_e32 v106, v108
	s_and_b32 s47, s36, 0xc000
	v_permlane32_swap_b32_e32 v107, v109
	s_add_i32 s47, s47, s31
	v_permlane32_swap_b32_e32 v110, v112
	v_permlane32_swap_b32_e32 v111, v113
	v_permlane32_swap_b32_e32 v134, v136
	v_permlane32_swap_b32_e32 v135, v137
	s_cmpk_gt_u32 s12, 0x80
	s_cselect_b64 s[10:11], -1, 0
	s_and_b64 vcc, exec, s[10:11]
	s_cbranch_vccnz .LBB0_776
	v_lshl_add_u64 v[246:247], s[42:43], 0, v[146:147]
	s_mov_b32 m0, s46
	s_nop 0
	global_load_lds_dwordx4 v[246:247], off
	v_lshl_add_u64 v[246:247], s[44:45], 0, v[142:143]
	s_mov_b32 m0, s47
	s_nop 0
	global_load_lds_dwordx4 v[246:247], off
	v_lshl_add_u64 v[246:247], s[42:43], 0, v[144:145]
	s_add_i32 m0, s46, 0x2000
	s_nop 0
	global_load_lds_dwordx4 v[246:247], off
	v_lshl_add_u64 v[246:247], s[44:45], 0, v[154:155]
	s_add_i32 m0, s47, 0x2000
	s_nop 0
	global_load_lds_dwordx4 v[246:247], off
; __device__ __forceinline__ void partialSM(f32x16& p0, f32x16& p1, float& m_reg, float& mn, float& alpha) {
;   constexpr float C = SCALE * 1.4426950408889634f;
;   float pmax = p0[0]; for (int r = 1; r < 16; ++r) pmax = fmaxf(pmax, p0[r]); for (int r = 0; r < 16; ++r) pmax = fmaxf(pmax, p1[r]);
;   { auto rr = __builtin_amdgcn_permlane32_swap(__float_as_uint(pmax), __float_as_uint(pmax), false, false);
;     pmax = fmaxf(__uint_as_float(rr[0]), __uint_as_float(rr[1])); }
;   if (__builtin_expect(__all(pmax - m_reg <= THR / SCALE), 1)) { mn = m_reg; alpha = 1.f; }
;   else { mn = fmaxf(m_reg, pmax); alpha = __builtin_amdgcn_exp2f((m_reg - mn) * C); m_reg = mn; }
;   float mnC = -mn * C;
;   for (int r = 0; r < 16; ++r) p0[r] = fmaf(p0[r], C, mnC); for (int r = 0; r < 16; ++r) p1[r] = fmaf(p1[r], C, mnC);
;   for (int r = 0; r < 16; ++r) p0[r] = __builtin_amdgcn_exp2f(p0[r]);
; }
; template <int D0> __device__ __forceinline__ void v_frag_read(VFrag& f, int vb) {
;   f.l0 = tr_read<v_rd_off(D0, 0, 0)>(vb); f.h0 = tr_read<v_rd_off(D0, 0, 1)>(vb); f.l1 = tr_read<v_rd_off(D0, 1, 0)>(vb); f.h1 = tr_read<v_rd_off(D0, 1, 1)>(vb);
;   f.l2 = tr_read<v_rd_off(D0, 2, 0)>(vb); f.h2 = tr_read<v_rd_off(D0, 2, 1)>(vb); f.l3 = tr_read<v_rd_off(D0, 3, 0)>(vb); f.h3 = tr_read<v_rd_off(D0, 3, 1)>(vb);
; }
; __device__ __forceinline__ void pv_mma(f32x16& od, const VFrag& f, bf16x8 pa0, bf16x8 pa1, bf16x8 pa2, bf16x8 pa3) {
;     ...
;   od = __builtin_amdgcn_mfma_f32_32x32x16_bf16(pa0, PK(f.l0, f.h0), od, 0, 0, 0);
;   od = __builtin_amdgcn_mfma_f32_32x32x16_bf16(pa1, PK(f.l1, f.h1), od, 0, 0, 0);
;   od = __builtin_amdgcn_mfma_f32_32x32x16_bf16(pa2, PK(f.l2, f.h2), od, 0, 0, 0);
;   od = __builtin_amdgcn_mfma_f32_32x32x16_bf16(pa3, PK(f.l3, f.h3), od, 0, 0, 0);
;     ...
; }
; __device__ __forceinline__ void pv_d0(f32x16* o, int vb, bf16x8 pa0, bf16x8 pa1, bf16x8 pa2, bf16x8 pa3) {
;   VFrag fa, fb;
;   v_frag_read<0>(fa, vb);
;   asm volatile("s_waitcnt lgkmcnt(0)" ::: "memory"); SBAR();
;   v_frag_read<1>(fb, vb); SBAR();
;   pv_mma(o[0], fa, pa0, pa1, pa2, pa3); SBAR();
;   asm volatile("s_waitcnt lgkmcnt(0)" ::: "memory"); SBAR();
;   v_frag_read<2>(fa, vb); SBAR();
;   pv_mma(o[1], fb, pa0, pa1, pa2, pa3); SBAR();
;   asm volatile("s_waitcnt lgkmcnt(0)" ::: "memory"); SBAR();
;   v_frag_read<3>(fb, vb); SBAR();
;   pv_mma(o[2], fa, pa0, pa1, pa2, pa3); SBAR();
.LBB0_776:
	ds_read_b64_tr_b16 v[204:205], v244 offset:0x200
	ds_read_b64_tr_b16 v[206:207], v244 offset:0xa00
	ds_read_b64_tr_b16 v[208:209], v244 offset:0x1200
	ds_read_b64_tr_b16 v[210:211], v244 offset:0x1a00
	ds_read_b64_tr_b16 v[212:213], v244 offset:0x2200
	ds_read_b64_tr_b16 v[214:215], v244 offset:0x2a00
	ds_read_b64_tr_b16 v[216:217], v244 offset:0x3200
	ds_read_b64_tr_b16 v[218:219], v244 offset:0x3a00
	v_mfma_f32_32x32x16_bf16 v[18:33], v[102:105], v[228:231], v[18:33]
	v_max_f32_e32 v245, v83, v83
	v_max_f32_e32 v246, v82, v82
	v_max_f32_e32 v245, v246, v245
	v_max3_f32 v245, v245, v84, v85
	v_max3_f32 v245, v245, v86, v87
	v_max3_f32 v245, v245, v88, v89
	v_max3_f32 v245, v245, v90, v91
	v_max3_f32 v245, v245, v92, v93
	v_mfma_f32_32x32x16_bf16 v[18:33], v[106:109], v[232:235], v[18:33]
	v_max3_f32 v245, v245, v94, v95
	v_max3_f32 v245, v245, v96, v97
	v_max3_f32 v245, v245, v66, v67
	v_max3_f32 v245, v245, v68, v69
	v_max3_f32 v245, v245, v70, v71
	v_max3_f32 v245, v245, v72, v73
	v_max3_f32 v245, v245, v74, v75
	v_max3_f32 v245, v245, v76, v77
	v_mfma_f32_32x32x16_bf16 v[18:33], v[110:113], v[236:239], v[18:33]
	v_max3_f32 v245, v245, v78, v79
	v_max3_f32 v245, v245, v80, v81
	v_mov_b32_e32 v246, v245
	s_nop 1
	v_permlane32_swap_b32_e32 v245, v246
	v_max_f32_e32 v246, v246, v246
	v_max_f32_e32 v245, v245, v245
	v_max_f32_e32 v245, v245, v246
	v_sub_f32_e32 v246, v245, v133
	v_mfma_f32_32x32x16_bf16 v[18:33], v[134:137], v[240:243], v[18:33]
	v_cmp_ge_f32_e32 vcc, s63, v246
	v_max_f32_e32 v246, v133, v133
	v_max_f32_e32 v245, v246, v245
	v_sub_f32_e32 v246, v133, v245
	v_mul_f32_e32 v246, 0x3e38aa3b, v246
	v_exp_f32_e32 v246, v246
	s_cmp_eq_u64 vcc, exec
	s_cselect_b64 s[0:1], -1, 0
	v_cndmask_b32_e64 v247, v246, 1.0, s[0:1]
	ds_read_b64_tr_b16 v[228:229], v244 offset:0x400
	ds_read_b64_tr_b16 v[230:231], v244 offset:0xc00
	ds_read_b64_tr_b16 v[232:233], v244 offset:0x1400
	ds_read_b64_tr_b16 v[234:235], v244 offset:0x1c00
	ds_read_b64_tr_b16 v[236:237], v244 offset:0x2400
	ds_read_b64_tr_b16 v[238:239], v244 offset:0x2c00
	ds_read_b64_tr_b16 v[240:241], v244 offset:0x3400
	ds_read_b64_tr_b16 v[242:243], v244 offset:0x3c00
	v_cndmask_b32_e64 v174, v245, v133, s[0:1]
	v_mul_f32_e32 v98, 0xbe38aa3b, v174
	s_waitcnt lgkmcnt(8)
	v_mfma_f32_32x32x16_bf16 v[50:65], v[102:105], v[204:207], v[50:65]
	v_fmamk_f32 v82, v82, 0x3e38aa3b, v98
	v_fmamk_f32 v83, v83, 0x3e38aa3b, v98
	v_fmamk_f32 v84, v84, 0x3e38aa3b, v98
	v_fmamk_f32 v85, v85, 0x3e38aa3b, v98
	v_mfma_f32_32x32x16_bf16 v[50:65], v[106:109], v[208:211], v[50:65]
	v_fmamk_f32 v86, v86, 0x3e38aa3b, v98
	v_fmamk_f32 v87, v87, 0x3e38aa3b, v98
	v_fmamk_f32 v88, v88, 0x3e38aa3b, v98
	v_fmamk_f32 v89, v89, 0x3e38aa3b, v98
	v_mfma_f32_32x32x16_bf16 v[50:65], v[110:113], v[212:215], v[50:65]
	v_fmamk_f32 v90, v90, 0x3e38aa3b, v98
	v_fmamk_f32 v91, v91, 0x3e38aa3b, v98
	v_fmamk_f32 v92, v92, 0x3e38aa3b, v98
	v_fmamk_f32 v93, v93, 0x3e38aa3b, v98
	v_mfma_f32_32x32x16_bf16 v[50:65], v[134:137], v[216:219], v[50:65]
	v_fmamk_f32 v94, v94, 0x3e38aa3b, v98
	v_fmamk_f32 v95, v95, 0x3e38aa3b, v98
	v_fmamk_f32 v96, v96, 0x3e38aa3b, v98
	v_fmamk_f32 v97, v97, 0x3e38aa3b, v98
	ds_read_b64_tr_b16 v[204:205], v244 offset:0x600
	ds_read_b64_tr_b16 v[206:207], v244 offset:0xe00
	ds_read_b64_tr_b16 v[208:209], v244 offset:0x1600
	ds_read_b64_tr_b16 v[210:211], v244 offset:0x1e00
	ds_read_b64_tr_b16 v[212:213], v244 offset:0x2600
	ds_read_b64_tr_b16 v[214:215], v244 offset:0x2e00
	ds_read_b64_tr_b16 v[216:217], v244 offset:0x3600
	ds_read_b64_tr_b16 v[218:219], v244 offset:0x3e00
	s_waitcnt lgkmcnt(8)
	v_mfma_f32_32x32x16_bf16 v[34:49], v[102:105], v[228:231], v[34:49]
	s_mov_b32 s46, 0x3e38aa3b
	v_pk_fma_f32 v[80:81], v[80:81], s[46:47], v[98:99] op_sel_hi:[1,0,0]
	v_pk_fma_f32 v[78:79], v[78:79], s[46:47], v[98:99] op_sel_hi:[1,0,0]
	v_mfma_f32_32x32x16_bf16 v[34:49], v[106:109], v[232:235], v[34:49]
	v_pk_fma_f32 v[76:77], v[76:77], s[46:47], v[98:99] op_sel_hi:[1,0,0]
	v_pk_fma_f32 v[74:75], v[74:75], s[46:47], v[98:99] op_sel_hi:[1,0,0]
	v_pk_fma_f32 v[72:73], v[72:73], s[46:47], v[98:99] op_sel_hi:[1,0,0]
	v_mfma_f32_32x32x16_bf16 v[34:49], v[110:113], v[236:239], v[34:49]
	v_pk_fma_f32 v[70:71], v[70:71], s[46:47], v[98:99] op_sel_hi:[1,0,0]
	v_pk_fma_f32 v[68:69], v[68:69], s[46:47], v[98:99] op_sel_hi:[1,0,0]
	v_pk_fma_f32 v[66:67], v[66:67], s[46:47], v[98:99] op_sel_hi:[1,0,0]
	v_mfma_f32_32x32x16_bf16 v[34:49], v[134:137], v[240:243], v[34:49]
	v_exp_f32_e32 v175, v82
	v_exp_f32_e32 v177, v83
	v_exp_f32_e32 v192, v84
	s_waitcnt lgkmcnt(0)
	v_mfma_f32_32x32x16_bf16 v[2:17], v[102:105], v[204:207], v[2:17]
	v_mov_b32_e32 v205, v247
	v_exp_f32_e32 v204, v97
	v_exp_f32_e32 v195, v85
	v_exp_f32_e32 v196, v86
	v_exp_f32_e32 v199, v87
	v_exp_f32_e32 v200, v88
	v_mfma_f32_32x32x16_bf16 v[2:17], v[106:109], v[208:211], v[2:17]
	v_exp_f32_e32 v203, v89
	v_exp_f32_e32 v176, v90
	v_exp_f32_e32 v193, v91
	v_exp_f32_e32 v194, v92
	v_mfma_f32_32x32x16_bf16 v[2:17], v[110:113], v[212:215], v[2:17]
	v_exp_f32_e32 v197, v93
	v_exp_f32_e32 v198, v94
	v_exp_f32_e32 v201, v95
	v_exp_f32_e32 v202, v96
	v_mfma_f32_32x32x16_bf16 v[2:17], v[134:137], v[216:219], v[2:17]
	v_cmp_gt_f32_e32 vcc, 1.0, v205
	s_cbranch_vccz .LBB0_780
	s_and_saveexec_b64 s[12:13], s[40:41]
	ds_write_b32 v162, v205 offset:128
	s_or_b64 exec, exec, s[12:13]
	s_waitcnt lgkmcnt(0)
	v_add_u32_e32 v101, s18, v140
	ds_read_b128 v[102:105], v101 offset:224
	ds_read_b128 v[106:109], v101 offset:192
	ds_read_b128 v[110:113], v101 offset:160
	ds_read_b128 v[134:137], v101 offset:128
	s_waitcnt lgkmcnt(0)
	v_pk_mul_f32 v[30:31], v[30:31], v[102:103]
	v_pk_mul_f32 v[26:27], v[26:27], v[106:107]
	v_pk_mul_f32 v[22:23], v[22:23], v[110:111]
	v_pk_mul_f32 v[32:33], v[32:33], v[104:105]
	v_pk_mul_f32 v[28:29], v[28:29], v[108:109]
	v_pk_mul_f32 v[24:25], v[24:25], v[112:113]
	v_pk_mul_f32 v[20:21], v[20:21], v[136:137]
	v_pk_mul_f32 v[18:19], v[18:19], v[134:135]
	v_pk_mul_f32 v[62:63], v[62:63], v[102:103]
	v_pk_mul_f32 v[58:59], v[58:59], v[106:107]
	v_pk_mul_f32 v[54:55], v[54:55], v[110:111]
	v_pk_mul_f32 v[64:65], v[64:65], v[104:105]
	v_pk_mul_f32 v[60:61], v[60:61], v[108:109]
	v_pk_mul_f32 v[56:57], v[56:57], v[112:113]
	v_pk_mul_f32 v[52:53], v[52:53], v[136:137]
	v_pk_mul_f32 v[50:51], v[50:51], v[134:135]
	v_pk_mul_f32 v[46:47], v[46:47], v[102:103]
	v_pk_mul_f32 v[42:43], v[42:43], v[106:107]
	v_pk_mul_f32 v[38:39], v[38:39], v[110:111]
	v_pk_mul_f32 v[48:49], v[48:49], v[104:105]
	v_pk_mul_f32 v[44:45], v[44:45], v[108:109]
	v_pk_mul_f32 v[40:41], v[40:41], v[112:113]
	v_pk_mul_f32 v[36:37], v[36:37], v[136:137]
	v_pk_mul_f32 v[34:35], v[34:35], v[134:135]
	v_pk_mul_f32 v[14:15], v[14:15], v[102:103]
	v_pk_mul_f32 v[10:11], v[10:11], v[106:107]
	v_pk_mul_f32 v[6:7], v[6:7], v[110:111]
	v_pk_mul_f32 v[16:17], v[16:17], v[104:105]
	v_pk_mul_f32 v[12:13], v[12:13], v[108:109]
	v_pk_mul_f32 v[8:9], v[8:9], v[112:113]
	v_pk_mul_f32 v[4:5], v[4:5], v[136:137]
	v_pk_mul_f32 v[2:3], v[2:3], v[134:135]
